# v19 + RoPE-table builder and lambda/bound builder moved from WG 1/2 (two adaLN units each) to the last two WGs (one adaLN unit each)
# baseline (speedup 1.0000x reference)
; #define LAS __attribute__((address_space(3)))
; __global__ void __launch_bounds__(512, 2) mega_fwd(Args args) {
;     ...
;     unsigned char* ws = args.ws;
;     float* MOD = (float*)(ws + WS_MOD);
;     float* TC64 = (float*)(ws + WS_TC64); float* TS64 = (float*)(ws + WS_TS64); float* TC128 = (float*)(ws + WS_TC128); float* TS128 = (float*)(ws + WS_TS128);
;     float* LAM = (float*)(ws + WS_LAM);
;     bf16_t* WIN = (bf16_t*)(ws + WS_WIN); bf16_t* WUP = (bf16_t*)(ws + WS_WUP); bf16_t* WBR = (bf16_t*)(ws + WS_WBR); bf16_t* WOUT = (bf16_t*)(ws + WS_WOUT);
;     bf16_t* H = (bf16_t*)(ws + WS_H); bf16_t* QA = (bf16_t*)(ws + WS_QA); bf16_t* KA = (bf16_t*)(ws + WS_KA); bf16_t* VA = (bf16_t*)(ws + WS_VA);
;     bf16_t* QB = (bf16_t*)(ws + WS_QB); bf16_t* KB = (bf16_t*)(ws + WS_KB); bf16_t* CKV = (bf16_t*)(ws + WS_CKV); bf16_t* VB = (bf16_t*)(ws + WS_VB);
;     bf16_t* QC = (bf16_t*)(ws + WS_QC); bf16_t* KC = (bf16_t*)(ws + WS_KC); bf16_t* VC = (bf16_t*)(ws + WS_VC);
;     bf16_t* GATE = (bf16_t*)(ws + WS_GATE); bf16_t* MRG = (bf16_t*)(ws + WS_MRG); bf16_t* BR = (bf16_t*)(ws + WS_BR); bf16_t* Y = (bf16_t*)(ws + WS_Y);
;     float* SS = (float*)(ws + WS_SS); float* CTXW = (float*)(ws + WS_CTXW); float* SCR = (float*)(ws + WS_SCR);
;     LAS float* xch = (LAS float*)(lds + XCH_OFF);
;     volatile LAS unsigned* bst = (volatile LAS unsigned*)(lds + XCH_OFF + 4096);
;     if (threadIdx.x < 2) bst[threadIdx.x] = 0u;
;     __syncthreads();
;     XcdBarrier bar = xcd_barrier_post((unsigned*)(ws + WS_BAR), bst);
.LBB0_6:
	s_add_u32 s4, s88, 0x78000
	s_addc_u32 s5, s89, 0
	v_writelane_b32 v251, s4, 8
	s_mov_b32 s11, 0
	v_lshrrev_b32_e32 v1, 20, v0
	v_writelane_b32 v251, s5, 9
	s_add_u32 s4, s88, 0x79000
	s_addc_u32 s5, s89, 0
	s_add_u32 s20, s88, 0x7a000
	v_writelane_b32 v251, s4, 10
	s_addc_u32 s21, s89, 0
	v_lshrrev_b32_e32 v0, 10, v0
	v_writelane_b32 v251, s5, 11
	s_add_u32 s4, s88, 0x7c000
	s_addc_u32 s5, s89, 0
	v_writelane_b32 v251, s4, 12
	v_or_b32_e32 v0, v0, v1
	v_mov_b32_e32 v177, 0
	v_writelane_b32 v251, s5, 13
	s_add_u32 s4, s88, 0x7e000
	s_addc_u32 s5, s89, 0
	v_writelane_b32 v251, s4, 14
	s_add_u32 s3, s88, 0xa4500
	v_mov_b32_e32 v189, 1
	v_writelane_b32 v251, s5, 15
	v_writelane_b32 v251, s3, 16
	s_addc_u32 s3, s89, 0
	v_writelane_b32 v251, s3, 17
	s_add_u32 s3, s88, 0xfca4500
	v_writelane_b32 v251, s3, 18
	s_addc_u32 s3, s89, 0
	v_writelane_b32 v251, s3, 19
	s_add_u32 s3, s88, 0x104a4500
	v_writelane_b32 v251, s3, 20
	s_addc_u32 s3, s89, 0
	v_writelane_b32 v251, s3, 21
	s_add_u32 s3, s88, 0x134a4500
	v_writelane_b32 v251, s3, 22
	s_addc_u32 s3, s89, 0
	s_add_u32 s4, s88, 0x154a4500
	v_writelane_b32 v251, s3, 23
	s_addc_u32 s5, s89, 0
	v_writelane_b32 v251, s4, 24
	v_mov_b32_e32 v178, 0x358637bd
	v_mov_b32_e32 v250, 0x3f4ccccd
	v_writelane_b32 v251, s5, 25
	s_add_u32 s4, s88, 0x198a4500
	s_addc_u32 s5, s89, 0
	v_writelane_b32 v251, s4, 26
	v_mov_b32_e32 v232, 0x260
	v_mov_b32_e32 v180, 0x413504f3
	v_writelane_b32 v251, s5, 27
	s_add_u32 s4, s88, 0x1baa4500
	s_addc_u32 s5, s89, 0
	v_writelane_b32 v251, s4, 28
	v_mov_b32_e32 v183, 0xbd93cd3a
	v_mov_b32_e32 v229, 0x7f800000
	v_writelane_b32 v251, s5, 29
	s_add_u32 s4, s88, 0x1c324500
	s_addc_u32 s5, s89, 0
	v_writelane_b32 v251, s4, 30
	v_mov_b32_e32 v230, 0x4400
	v_mov_b32_e32 v231, 0x31c
	v_writelane_b32 v251, s5, 31
	s_add_u32 s4, s88, 0x1cba4500
	s_addc_u32 s5, s89, 0
	v_writelane_b32 v251, s4, 32
	v_mov_b32_e32 v233, 0x7c80000
	s_movk_i32 s95, 0x100
	v_writelane_b32 v251, s5, 33
	s_add_u32 s4, s88, 0x1fea4500
	s_addc_u32 s5, s89, 0
	v_writelane_b32 v251, s4, 34
	s_mov_b32 s92, 0x1e000
	s_movk_i32 s84, 0x2000
	v_writelane_b32 v251, s5, 35
	s_add_u32 s4, s88, 0x231a4500
	s_addc_u32 s5, s89, 0
	v_writelane_b32 v251, s4, 36
	s_mov_b32 s85, 0x12000
	s_movk_i32 s82, 0x6000
	v_writelane_b32 v251, s5, 37
	s_add_u32 s4, s88, 0x242a4500
	s_addc_u32 s5, s89, 0
	v_writelane_b32 v251, s4, 38
	s_mov_b32 s76, 0x18000
	s_mov_b32 s77, 0xc000
	v_writelane_b32 v251, s5, 39
	s_add_u32 s4, s88, 0x264a4500
	s_addc_u32 s5, s89, 0
	v_writelane_b32 v251, s4, 40
	s_mov_b32 s91, 0x24000
	s_mov_b32 s83, 0x60000
	v_writelane_b32 v251, s5, 41
	s_add_u32 s4, s88, 0x286a4500
	s_addc_u32 s5, s89, 0
	v_writelane_b32 v251, s4, 42
	s_movk_i32 s40, 0x3000
	s_mov_b32 s94, 0x2a000
	v_writelane_b32 v251, s5, 43
	s_add_u32 s4, s88, 0x2a8a4500
	s_addc_u32 s5, s89, 0
	v_writelane_b32 v251, s4, 44
	s_mov_b32 s93, 0x30000
	s_mov_b32 s34, 0x90000
	v_writelane_b32 v251, s5, 45
	s_add_u32 s4, s88, 0x2caa4500
	s_addc_u32 s5, s89, 0
	s_add_u32 s38, s88, 0x330a4500
	v_writelane_b32 v251, s4, 46
	s_addc_u32 s39, s89, 0
	s_mov_b64 s[22:23], 0x20000
	v_writelane_b32 v251, s5, 47
	s_add_u32 s4, s88, 0x3fca4500
	s_addc_u32 s5, s89, 0
	s_add_u32 s18, s88, 0x462a4500
	v_writelane_b32 v251, s4, 48
	s_addc_u32 s19, s89, 0
	s_mov_b64 s[72:73], 0x800
	v_writelane_b32 v251, s5, 49
	s_add_u32 s4, s88, 0x4a6a4500
	s_addc_u32 s5, s89, 0
	v_writelane_b32 v251, s4, 50
	s_add_u32 s3, s88, 0x4a72c500
	s_mov_b64 s[96:97], 0x60000
	v_writelane_b32 v251, s5, 51
	v_writelane_b32 v251, s3, 52
	s_addc_u32 s3, s89, 0
	v_writelane_b32 v251, s3, 53
	s_and_b32 s3, s78, 7
	s_cmp_eq_u32 s3, 0
	s_cselect_b64 s[4:5], -1, 0
	v_writelane_b32 v251, s4, 54
	s_ashr_i32 s3, s78, 3
	s_mov_b64 s[86:87], 0x90000
	v_writelane_b32 v251, s5, 55
	v_writelane_b32 v251, s3, 56
	s_add_u32 s3, s88, 0x82100
	v_writelane_b32 v251, s3, 57
	s_addc_u32 s3, s89, 0
	v_writelane_b32 v251, s3, 58
	s_cmpk_eq_i32 s78, 0x100
	v_readlane_b32 s12, v251, 0
	v_readlane_b32 s13, v251, 1
	s_load_dword s3, s[12:13], 0x100
	s_cselect_b64 s[14:15], -1, 0
	s_cmpk_lg_i32 s78, 0x100
	s_cselect_b64 s[4:5], -1, 0
	v_writelane_b32 v251, s4, 59
	s_waitcnt lgkmcnt(0)
	s_cmp_lg_u32 s3, 0
	s_load_dwordx16 s[52:67], s[12:13], 0x40
	v_writelane_b32 v251, s5, 60
	s_cselect_b64 s[4:5], -1, 0
	s_ashr_i32 s79, s78, 31
	v_writelane_b32 v251, s4, 61
	s_and_b64 s[16:17], s[14:15], s[4:5]
	s_cmp_eq_u32 s3, 0
	v_writelane_b32 v251, s5, 62
	s_cselect_b64 s[8:9], -1, 0
	s_add_u32 s4, s88, 0x7e300
	s_addc_u32 s5, s89, 0
	v_writelane_b32 v251, s4, 63
	s_mov_b32 s3, s11
	s_mov_b64 s[24:25], 0x160000
	v_writelane_b32 v252, s5, 0
	s_add_u32 s4, s88, 0x7e500
	s_addc_u32 s5, s89, 0
	v_writelane_b32 v252, s4, 1
	s_load_dwordx4 s[28:31], s[12:13], 0xe0
	s_nop 0
	v_writelane_b32 v252, s5, 2
	s_add_u32 s4, s88, 0x7e600
	s_addc_u32 s5, s89, 0
	v_writelane_b32 v252, s4, 3
	s_nop 1
	v_writelane_b32 v252, s5, 4
	s_add_u32 s4, s88, 0x7e700
	s_addc_u32 s5, s89, 0
	v_writelane_b32 v252, s4, 5
	s_nop 1
	v_writelane_b32 v252, s5, 6
	s_add_u32 s4, s88, 0x7e800
	s_addc_u32 s5, s89, 0
	v_writelane_b32 v252, s4, 7
	s_nop 1
	v_writelane_b32 v252, s5, 8
	s_add_u32 s4, s88, 0x7e900
	s_addc_u32 s5, s89, 0
	v_writelane_b32 v252, s4, 9
	s_nop 1
	v_writelane_b32 v252, s5, 10
	s_add_u32 s4, s88, 0x7ea00
	s_addc_u32 s5, s89, 0
	v_writelane_b32 v252, s4, 11
	s_nop 1
	v_writelane_b32 v252, s5, 12
	s_add_u32 s4, s88, 0x7eb00
	s_addc_u32 s5, s89, 0
	v_writelane_b32 v252, s4, 13
	s_nop 1
	v_writelane_b32 v252, s5, 14
	s_add_u32 s4, s88, 0x7ec00
	s_addc_u32 s5, s89, 0
	v_writelane_b32 v252, s4, 15
	s_nop 1
	v_writelane_b32 v252, s5, 16
	s_add_u32 s4, s88, 0x7ed00
; #define LAS __attribute__((address_space(3)))
; __device__ __forceinline__ unsigned xb_ld(unsigned* p)              { return __hip_atomic_load(p, __ATOMIC_RELAXED, __HIP_MEMORY_SCOPE_AGENT); }
; __device__ __forceinline__ unsigned xb_add(unsigned* p, unsigned v) { return __hip_atomic_fetch_add(p, v, __ATOMIC_RELAXED, __HIP_MEMORY_SCOPE_AGENT); }
; __device__ __forceinline__ unsigned xb_xcc_id() { return (unsigned)__builtin_amdgcn_s_getreg((3 << 11) | 20) & 0xFu; }
; __device__ __forceinline__ XcdBarrier xcd_barrier_post(unsigned* bar, volatile LAS unsigned* st) {
;     XcdBarrier b; b.bar = bar; b.x = xb_xcc_id(); b.st = st;
;     if (threadIdx.x == 0) (void)xb_add(&bar[XB_XCNT(b.x)], 1u);
;     return b;
; }
; __device__ __forceinline__ void xcd_barrier_complete(unsigned* bar, unsigned x, unsigned& nloc, unsigned& nx) {
;     const unsigned G = gridDim.x * gridDim.y * gridDim.z;
;     unsigned sum, cnt, mine, sp = 0u;
;     for (;;) {
;         sum = 0u; cnt = 0u; mine = 0u;
; #pragma unroll
;         for (unsigned j = 0; j < 16; ++j) { const unsigned c = xb_ld(&bar[XB_XCNT(j)]); sum += c; cnt += (c > 0u) ? 1u : 0u; mine = (j == x) ? c : mine; }
	s_addc_u32 s5, s89, 0
	v_writelane_b32 v252, s4, 17
	s_nop 1
	v_writelane_b32 v252, s5, 18
	s_add_u32 s4, s88, 0x7ee00
	s_addc_u32 s5, s89, 0
	v_writelane_b32 v252, s4, 19
	s_nop 1
	v_writelane_b32 v252, s5, 20
	s_add_u32 s4, s88, 0x7ef00
	s_addc_u32 s5, s89, 0
	v_writelane_b32 v252, s4, 21
	s_nop 1
	v_writelane_b32 v252, s5, 22
	s_add_u32 s4, s88, 0x7f000
	s_addc_u32 s5, s89, 0
	v_writelane_b32 v252, s4, 23
	s_nop 1
	v_writelane_b32 v252, s5, 24
	s_add_u32 s4, s88, 0x7f100
	s_addc_u32 s5, s89, 0
	v_writelane_b32 v252, s4, 25
	s_nop 1
	v_writelane_b32 v252, s5, 26
	s_add_u32 s4, s88, 0x7f200
	s_addc_u32 s5, s89, 0
	v_writelane_b32 v252, s4, 27
	s_nop 1
	v_writelane_b32 v252, s5, 28
	s_add_u32 s4, s88, 0x7f300
	s_addc_u32 s5, s89, 0
	v_writelane_b32 v252, s4, 29
	s_nop 1
	v_writelane_b32 v252, s5, 30
	s_add_u32 s4, s88, 0x7f400
	s_addc_u32 s5, s89, 0
	v_writelane_b32 v252, s4, 31
	s_cmp_eq_u32 s6, 15
	s_nop 0
	v_writelane_b32 v252, s5, 32
	s_cselect_b64 s[4:5], -1, 0
	v_writelane_b32 v252, s4, 33
	s_cmp_eq_u32 s6, 14
	s_nop 0
	v_writelane_b32 v252, s5, 34
	s_cselect_b64 s[4:5], -1, 0
	v_writelane_b32 v252, s4, 35
	s_cmp_eq_u32 s6, 13
	s_nop 0
	v_writelane_b32 v252, s5, 36
	s_cselect_b64 s[4:5], -1, 0
	v_writelane_b32 v252, s4, 37
	s_cmp_eq_u32 s6, 12
	s_nop 0
	v_writelane_b32 v252, s5, 38
	s_cselect_b64 s[4:5], -1, 0
	v_writelane_b32 v252, s4, 39
	s_cmp_eq_u32 s6, 11
	s_nop 0
	v_writelane_b32 v252, s5, 40
	s_cselect_b64 s[4:5], -1, 0
	v_writelane_b32 v252, s4, 41
	s_cmp_eq_u32 s6, 10
	s_nop 0
	v_writelane_b32 v252, s5, 42
	s_cselect_b64 s[4:5], -1, 0
	v_writelane_b32 v252, s4, 43
	s_cmp_eq_u32 s6, 9
	s_nop 0
	v_writelane_b32 v252, s5, 44
	s_cselect_b64 s[4:5], -1, 0
	v_writelane_b32 v252, s4, 45
	s_cmp_eq_u32 s6, 8
	s_nop 0
	v_writelane_b32 v252, s5, 46
	s_cselect_b64 s[4:5], -1, 0
	v_writelane_b32 v252, s4, 47
	s_cmp_eq_u32 s6, 7
	s_nop 0
	v_writelane_b32 v252, s5, 48
	s_cselect_b64 s[4:5], -1, 0
	v_writelane_b32 v252, s4, 49
	s_cmp_eq_u32 s6, 6
	s_nop 0
	v_writelane_b32 v252, s5, 50
	s_cselect_b64 s[4:5], -1, 0
	v_writelane_b32 v252, s4, 51
	s_cmp_eq_u32 s6, 5
	s_nop 0
	v_writelane_b32 v252, s5, 52
	s_cselect_b64 s[4:5], -1, 0
	v_writelane_b32 v252, s4, 53
	s_cmp_eq_u32 s6, 4
	s_nop 0
	v_writelane_b32 v252, s5, 54
	s_cselect_b64 s[4:5], -1, 0
	v_writelane_b32 v252, s4, 55
	s_cmp_eq_u32 s6, 3
	s_nop 0
	v_writelane_b32 v252, s5, 56
	s_cselect_b64 s[4:5], -1, 0
	v_writelane_b32 v252, s4, 57
	s_cmp_eq_u32 s6, 2
	s_nop 0
	v_writelane_b32 v252, s5, 58
	s_cselect_b64 s[4:5], -1, 0
	v_writelane_b32 v252, s4, 59
	s_cmp_eq_u32 s6, 1
	s_nop 0
	v_writelane_b32 v252, s5, 60
	s_cselect_b64 s[4:5], -1, 0
	v_writelane_b32 v252, s4, 61
	s_cmp_eq_u32 s6, 0
	s_nop 0
	v_writelane_b32 v252, s5, 62
	s_cselect_b64 s[4:5], -1, 0
	v_writelane_b32 v252, s4, 63
	s_nop 1
	v_writelane_b32 v253, s5, 0
	s_lshl_b32 s4, s6, 8
	s_add_u32 s0, s0, s4
	s_addc_u32 s1, s1, 0
	s_add_u32 s4, s0, 0x1400
	s_addc_u32 s5, s1, 0
	v_writelane_b32 v253, s4, 1
	s_add_u32 s0, s0, 0x2400
	s_addc_u32 s1, s1, 0
	v_writelane_b32 v253, s5, 2
	v_writelane_b32 v253, s0, 3
	s_mov_b64 s[6:7], 0x30000
	s_nop 0
	v_writelane_b32 v253, s1, 4
	s_add_u32 s0, s88, 0x81500
	s_addc_u32 s1, s89, 0
	v_writelane_b32 v253, s0, 5
	s_nop 1
	v_writelane_b32 v253, s1, 6
	s_add_u32 s0, s88, 0x81600
	s_addc_u32 s1, s89, 0
	v_writelane_b32 v253, s0, 7
	s_nop 1
	v_writelane_b32 v253, s1, 8
	s_mov_b32 s0, s2
	v_writelane_b32 v253, s0, 9
	s_nop 1
	v_writelane_b32 v253, s1, 10
	s_lshl_b64 s[0:1], s[2:3], 17
	s_add_u32 s0, s88, s0
	s_addc_u32 s1, s89, s1
	s_add_u32 s0, s0, 0x4af2c500
	s_addc_u32 s1, s1, 0
	v_writelane_b32 v253, s0, 11
	s_nop 1
	v_writelane_b32 v253, s1, 12
	s_movk_i32 s0, 0x3ff
	v_writelane_b32 v253, s14, 13
	v_and_or_b32 v0, v0, s0, v179
	s_nor_b64 s[0:1], s[14:15], s[8:9]
	v_writelane_b32 v253, s15, 14
	v_writelane_b32 v253, s0, 15
	s_mov_b32 s8, 0x20000
	s_movk_i32 s9, 0x200
	v_writelane_b32 v253, s1, 16
	s_lshl_b32 s0, s78, 3
	v_writelane_b32 v253, s16, 17
	s_xor_b64 s[2:3], s[16:17], -1
	s_nop 0
	v_writelane_b32 v253, s17, 18
	s_mov_b32 s16, s0
	v_readlane_b32 s0, v251, 4
	v_readlane_b32 s1, v251, 5
	v_writelane_b32 v253, s2, 19
	s_nor_b64 s[0:1], s[0:1], s[2:3]
	s_nop 0
	v_writelane_b32 v253, s3, 20
	v_writelane_b32 v253, s0, 21
	s_nop 1
	v_writelane_b32 v253, s1, 22
	s_add_u32 s0, s88, 0x4272c500
	v_writelane_b32 v253, s0, 23
	s_addc_u32 s0, s89, 0
	s_waitcnt lgkmcnt(0)
; __global__ void __launch_bounds__(512, 2) mega_fwd(Args args) {
;     ...
;             if (bx == 1 % G) {
;                 for (int i = tid; i < 64 * 16; i += 512) { const int pos = i >> 4, f = i & 15; const float ang = (float)pos * INVF32[f]; float s, c; sincos_d((double)ang, s, c); TC64[i] = c; TS64[i] = s; }
;                 for (int i = tid; i < 64 * 32; i += 512) { const int pos = i >> 5, f = i & 31; const float ang = (float)pos * INVF64[f]; float s, c; sincos_d((double)ang, s, c); TC128[i] = c; TS128[i] = s; }
;             }
;             if (bx == 2 % G && tid < DEPTH) {
	s_cmp_lg_u64 s[62:63], 0
	v_writelane_b32 v253, s0, 24
	s_cselect_b64 s[0:1], -1, 0
	v_writelane_b32 v253, s0, 25
	s_nop 1
	v_writelane_b32 v253, s1, 26
	s_abs_i32 s0, s78
	v_cvt_f32_u32_e32 v1, s0
	s_sub_i32 s1, 0, s0
	v_rcp_iflag_f32_e32 v1, v1
	s_nop 0
	v_mul_f32_e32 v1, 0x4f7ffffe, v1
	v_cvt_u32_f32_e32 v1, v1
	s_nop 0
	v_readfirstlane_b32 s2, v1
	s_mul_i32 s1, s1, s2
	s_mul_hi_u32 s1, s2, s1
	s_add_i32 s2, s2, s1
	s_sub_i32 s1, 1, s0
	s_cmp_lt_u32 s0, 2
	s_cselect_b32 s1, s1, 1
	s_sub_i32 s3, s1, s0
	s_cmp_ge_u32 s1, s0
	s_cselect_b32 s1, s3, s1
	s_sub_i32 s1, s0, 1
	v_writelane_b32 v253, s1, 27
	s_lshr_b32 s1, s2, 31
	s_mul_i32 s1, s1, s0
	s_sub_i32 s1, 2, s1
	s_sub_i32 s2, s1, s0
	s_cmp_ge_u32 s1, s0
	s_cselect_b32 s1, s2, s1
	s_sub_i32 s2, s1, s0
	s_cmp_ge_u32 s1, s0
	s_cselect_b32 s0, s2, s1
	s_sub_i32 s0, s78, 2
	s_max_i32 s0, s0, 0
	v_writelane_b32 v253, s0, 28
	s_add_u32 s0, s88, 0x154a5300
	v_writelane_b32 v253, s0, 29
	s_addc_u32 s0, s89, 0
	v_writelane_b32 v253, s0, 30
	s_add_u32 s0, s62, 0xffff0440
	v_writelane_b32 v253, s0, 31
	v_writelane_b32 v253, s52, 32
	s_addc_u32 s0, s63, -1
	s_mov_b32 s3, 0xc01921fb
	v_writelane_b32 v253, s53, 33
	v_writelane_b32 v253, s54, 34
	v_writelane_b32 v253, s55, 35
	v_writelane_b32 v253, s56, 36
	v_writelane_b32 v253, s57, 37
	v_writelane_b32 v253, s58, 38
	v_writelane_b32 v253, s59, 39
	v_writelane_b32 v253, s60, 40
	v_writelane_b32 v253, s61, 41
	v_writelane_b32 v253, s62, 42
	v_writelane_b32 v253, s63, 43
	v_writelane_b32 v253, s64, 44
	v_writelane_b32 v253, s65, 45
	v_writelane_b32 v253, s66, 46
	v_writelane_b32 v253, s67, 47
	v_writelane_b32 v253, s0, 48
	s_add_i32 s0, 0, 0x21000
	v_writelane_b32 v253, s0, 49
	s_add_i32 s0, 0, 0x21004
	v_writelane_b32 v253, s0, 50
	s_load_dwordx16 s[52:67], s[12:13], 0x0
	v_cmp_eq_u32_e64 s[0:1], 0, v0
	v_mbcnt_lo_u32_b32 v1, -1, 0
	v_mbcnt_hi_u32_b32 v228, -1, v1
	v_writelane_b32 v253, s0, 51
	s_nop 1
	v_writelane_b32 v253, s1, 52
	v_writelane_b32 v253, s2, 53
	s_mov_b64 s[0:1], 0x80
	s_nop 0
	v_writelane_b32 v253, s3, 54
	s_load_dwordx2 s[2:3], s[12:13], 0xc0
	s_waitcnt lgkmcnt(0)
	v_writelane_b32 v253, s2, 55
	s_nop 1
	v_writelane_b32 v253, s3, 56
	v_writelane_b32 v253, s28, 57
	s_nop 1
	v_writelane_b32 v253, s29, 58
	v_writelane_b32 v253, s30, 59
	v_writelane_b32 v253, s31, 60
	v_writelane_b32 v253, s52, 61
	s_nop 1
	v_writelane_b32 v254, s55, 0
	v_writelane_b32 v254, s56, 1
	v_writelane_b32 v254, s57, 2
	v_writelane_b32 v254, s58, 3
	v_writelane_b32 v254, s59, 4
	v_writelane_b32 v254, s60, 5
	v_writelane_b32 v254, s61, 6
	v_writelane_b32 v254, s62, 7
	v_writelane_b32 v254, s63, 8
	v_writelane_b32 v254, s64, 9
	v_writelane_b32 v254, s65, 10
	v_writelane_b32 v253, s53, 62
	v_writelane_b32 v254, s66, 11
	v_writelane_b32 v253, s54, 63
	v_writelane_b32 v254, s67, 12
	s_load_dwordx16 s[52:67], s[12:13], 0x80
	s_waitcnt lgkmcnt(0)
	v_writelane_b32 v254, s52, 13
	s_nop 1
	v_writelane_b32 v254, s53, 14
	v_writelane_b32 v254, s54, 15
	v_writelane_b32 v254, s55, 16
	v_writelane_b32 v254, s56, 17
	v_writelane_b32 v254, s57, 18
	v_writelane_b32 v254, s58, 19
	v_writelane_b32 v254, s59, 20
	v_writelane_b32 v254, s60, 21
	v_writelane_b32 v254, s61, 22
	v_writelane_b32 v254, s62, 23
	v_writelane_b32 v254, s63, 24
	v_writelane_b32 v254, s64, 25
	v_writelane_b32 v254, s65, 26
	v_writelane_b32 v254, s66, 27
	v_writelane_b32 v254, s67, 28
	v_writelane_b32 v254, s78, 29
	s_nop 1
	v_writelane_b32 v254, s79, 30
	v_writelane_b32 v254, s20, 31
	s_nop 1
	v_writelane_b32 v254, s21, 32
	v_writelane_b32 v254, s16, 33
	s_branch .LBB0_11
